# barrier wait: parked workgroups re-read the four kernel-argument cache lines (phases start with scalar kernarg loads right after the invalidate); kvc flags packed into one SGPR
# baseline (speedup 1.0000x reference)
; #define LAS __attribute__((address_space(3)))
; #define WSB(T, off) ((T*)(kargs()->ws + (off)))
; __global__ void __launch_bounds__(NT, 2) mega(Args a_unused) {
;     extern __shared__ __attribute__((aligned(16))) unsigned char lds[];
;     volatile LAS unsigned* bst = (volatile LAS unsigned*)((LAS unsigned char*)lds + LDS_BYTES - 16);
;     if (threadIdx.x < 4) bst[threadIdx.x] = 0u;
;     __syncthreads();
;     XcdBarrier bar = xcd_barrier_post(WSB(unsigned, WS_BAR), bst);
_Z4mega4Args:
	s_mov_b32 s100, 0
	v_cmp_gt_u32_e32 vcc, 4, v0
	s_and_saveexec_b64 s[4:5], vcc
	v_lshl_add_u32 v1, v0, 2, 0
	v_add_u32_e32 v1, 0x23ff0, v1
	v_mov_b32_e32 v2, 0
	ds_write_b32 v1, v2
	s_or_b64 exec, exec, s[4:5]
	s_mov_b64 s[6:7], s[0:1]
	s_waitcnt lgkmcnt(0)
	s_barrier
	s_getreg_b32 s3, hwreg(HW_REG_XCC_ID, 0, 4)
	s_and_b32 s33, s3, 15
	v_cmp_eq_u32_e64 s[40:41], 0, v0
	s_and_saveexec_b64 s[4:5], s[40:41]
	s_cbranch_execz .LBB0_5
	s_mov_b64 s[8:9], exec
	v_mbcnt_lo_u32_b32 v1, s8, 0
	v_mbcnt_hi_u32_b32 v1, s9, v1
	v_cmp_eq_u32_e32 vcc, 0, v1
	s_and_b64 s[10:11], exec, vcc
	s_mov_b64 exec, s[10:11]
	s_cbranch_execz .LBB0_5
	s_load_dwordx2 s[6:7], s[6:7], 0xf8
	s_lshl_b32 s3, s33, 8
	v_mov_b32_e32 v1, 0xc0000
	s_waitcnt lgkmcnt(0)
	s_add_u32 s6, s6, s3
	s_addc_u32 s7, s7, 0
	s_bcnt1_i32_b64 s3, s[8:9]
	v_mov_b32_e32 v2, s3
	global_atomic_add v1, v2, s[6:7] offset:1024

; __device__ __forceinline__ unsigned xb_ld(unsigned* p)              { return __hip_atomic_load(p, __ATOMIC_RELAXED, __HIP_MEMORY_SCOPE_AGENT); }
; __device__ __forceinline__ unsigned xb_add(unsigned* p, unsigned v) { return __hip_atomic_fetch_add(p, v, __ATOMIC_RELAXED, __HIP_MEMORY_SCOPE_AGENT); }
; #define XB_SPIN(cond, bar) do { unsigned _sp = 0; while (cond) { __builtin_amdgcn_s_sleep(1); \
;     if ((++_sp & 255u) == 0u) { if (xb_ld(&(bar)[XB_TMO])) break; if (_sp > XB_SPIN_CAP) { atomicAdd(&(bar)[XB_TMO], 1u); break; } } } } while (0)
; __device__ __forceinline__ void xcd_barrier(const XcdBarrier& b) {
;     ...
;         unsigned nloc = b.st[0], nx = b.st[1];
;         if (nloc == 0u) { xcd_barrier_complete(bar, b.x, nloc, nx); b.st[0] = nloc; b.st[1] = nx; }
;         const unsigned old = xb_add(&bar[XB_XSUB(b.x)], 1u);
;         const unsigned gen = old / nloc;
;         if (old + 1u == (gen + 1u) * nloc) {
;             __builtin_amdgcn_fence(__ATOMIC_RELEASE, "agent");
;             asm volatile("s_waitcnt vmcnt(0)" ::: "memory");
;             const unsigned og = xb_add(&bar[XB_TOP], 1u);
;             const unsigned tg = og / nx;
;             if (og + 1u == (tg + 1u) * nx) xb_add(&bar[XB_TOPGEN], 1u);
;             else XB_SPIN(xb_ld(&bar[XB_TOPGEN]) == tg, bar);
;             __builtin_amdgcn_fence(__ATOMIC_ACQUIRE, "agent");
;             xb_add(&bar[XB_XGEN(b.x)], 1u);
;             asm volatile("s_waitcnt vmcnt(0)" ::: "memory");
;         } else {
;             XB_SPIN(xb_ld(&bar[XB_XGEN(b.x)]) == gen, bar);
;             __builtin_amdgcn_fence(__ATOMIC_ACQUIRE, "agent");
;             asm volatile("s_waitcnt vmcnt(0)" ::: "memory");
.LBB0_145:
	s_or_b64 exec, exec, s[10:11]
	v_cvt_f32_u32_e32 v5, v3
	s_waitcnt vmcnt(0)
	v_readfirstlane_b32 s8, v4
	v_sub_u32_e32 v4, 0, v3
	v_rcp_iflag_f32_e32 v5, v5
	v_add_u32_e32 v6, s8, v2
	v_mul_f32_e32 v5, 0x4f7ffffe, v5
	v_cvt_u32_f32_e32 v5, v5
	v_mul_lo_u32 v2, v4, v5
	v_mul_hi_u32 v2, v5, v2
	v_add_u32_e32 v2, v5, v2
	v_mul_hi_u32 v2, v6, v2
	v_mul_lo_u32 v4, v2, v3
	v_sub_u32_e32 v4, v6, v4
	v_add_u32_e32 v5, 1, v2
	v_cmp_ge_u32_e32 vcc, v4, v3
	s_nop 1
	v_cndmask_b32_e32 v2, v2, v5, vcc
	v_sub_u32_e32 v5, v4, v3
	v_cndmask_b32_e32 v4, v4, v5, vcc
	v_add_u32_e32 v5, 1, v2
	v_cmp_ge_u32_e32 vcc, v4, v3
	v_add_u32_e32 v4, 1, v6
	s_nop 0
	v_cndmask_b32_e32 v2, v2, v5, vcc
	v_mul_lo_u32 v5, v3, v2
	v_add_u32_e32 v3, v5, v3
	v_mad_u32_u24 v255, v2, v1, v1
	v_cmp_ne_u32_e32 vcc, v4, v3
	s_and_saveexec_b64 s[8:9], vcc
	s_xor_b64 s[8:9], exec, s[8:9]
	s_cbranch_execz .LBB0_159
	buffer_inv sc1
	s_add_i32 s10, s28, 0x900
	s_mov_b32 s11, 0
	s_lshl_b64 s[10:11], s[10:11], 2
	s_add_u32 s14, s26, s10
	s_addc_u32 s15, s27, s11
	s_waitcnt lgkmcnt(0)
	v_mov_b32_e32 v1, 0
	global_load_dword v3, v1, s[14:15] sc1
	s_load_dword s101, s[0:1], 0x0
	s_load_dword s101, s[0:1], 0x40
	s_load_dword s101, s[0:1], 0x80
	s_load_dword s101, s[0:1], 0xc0
	s_waitcnt vmcnt(0)
	v_cmp_lt_u32_e32 vcc, v3, v255
	s_and_saveexec_b64 s[10:11], vcc
	s_cbranch_execz .LBB0_158
	s_add_u32 s12, s6, 0xc0200
	s_addc_u32 s13, s7, 0
	s_mov_b32 s29, 1
	s_mov_b64 s[16:17], 0
	s_branch .LBB0_149

; __device__ __forceinline__ unsigned xb_ld(unsigned* p)              { return __hip_atomic_load(p, __ATOMIC_RELAXED, __HIP_MEMORY_SCOPE_AGENT); }
; __device__ __forceinline__ unsigned xb_add(unsigned* p, unsigned v) { return __hip_atomic_fetch_add(p, v, __ATOMIC_RELAXED, __HIP_MEMORY_SCOPE_AGENT); }
; #define XB_SPIN(cond, bar) do { unsigned _sp = 0; while (cond) { __builtin_amdgcn_s_sleep(1); \
;     if ((++_sp & 255u) == 0u) { if (xb_ld(&(bar)[XB_TMO])) break; if (_sp > XB_SPIN_CAP) { atomicAdd(&(bar)[XB_TMO], 1u); break; } } } } while (0)
; __device__ __forceinline__ void xcd_barrier(const XcdBarrier& b) {
;     ...
;         if (old + 1u == (gen + 1u) * nloc) {
;             __builtin_amdgcn_fence(__ATOMIC_RELEASE, "agent");
;             asm volatile("s_waitcnt vmcnt(0)" ::: "memory");
;             const unsigned og = xb_add(&bar[XB_TOP], 1u);
;             const unsigned tg = og / nx;
;             if (og + 1u == (tg + 1u) * nx) xb_add(&bar[XB_TOPGEN], 1u);
;             else XB_SPIN(xb_ld(&bar[XB_TOPGEN]) == tg, bar);
;             __builtin_amdgcn_fence(__ATOMIC_ACQUIRE, "agent");
;             xb_add(&bar[XB_XGEN(b.x)], 1u);
;             asm volatile("s_waitcnt vmcnt(0)" ::: "memory");
.LBB0_159:
	s_andn2_saveexec_b64 s[8:9], s[8:9]
	s_cbranch_execz .LBB0_179
	s_mov_b64 s[8:9], exec
	buffer_wbl2 sc1
	buffer_inv sc1
	s_waitcnt lgkmcnt(0)
	s_waitcnt vmcnt(0)
	v_mbcnt_lo_u32_b32 v2, s8, 0
	v_mbcnt_hi_u32_b32 v2, s9, v2
	v_cmp_eq_u32_e32 vcc, 0, v2
	s_and_saveexec_b64 s[10:11], vcc
	s_cbranch_execz .LBB0_162
	s_bcnt1_i32_b64 s8, s[8:9]
	v_mov_b32_e32 v3, 0xc2400
	v_mov_b32_e32 v4, s8
	global_atomic_add v3, v4, s[6:7]
	global_atomic_add v3, v4, s[6:7] offset:256
	global_atomic_add v3, v4, s[6:7] offset:512
	global_atomic_add v3, v4, s[6:7] offset:768
	global_atomic_add v3, v4, s[6:7] offset:1024
	global_atomic_add v3, v4, s[6:7] offset:1280
	global_atomic_add v3, v4, s[6:7] offset:1536
	global_atomic_add v3, v4, s[6:7] offset:1792
	global_atomic_add v3, v4, s[6:7] offset:2048
	global_atomic_add v3, v4, s[6:7] offset:2304
	global_atomic_add v3, v4, s[6:7] offset:2560
	global_atomic_add v3, v4, s[6:7] offset:2816
	global_atomic_add v3, v4, s[6:7] offset:3072
	global_atomic_add v3, v4, s[6:7] offset:3328
	global_atomic_add v3, v4, s[6:7] offset:3584
	global_atomic_add v3, v4, s[6:7] offset:3840
	s_load_dword s101, s[0:1], 0x0
	s_load_dword s101, s[0:1], 0x40
	s_load_dword s101, s[0:1], 0x80
	s_load_dword s101, s[0:1], 0xc0

; __device__ __forceinline__ unsigned xb_ld(unsigned* p)              { return __hip_atomic_load(p, __ATOMIC_RELAXED, __HIP_MEMORY_SCOPE_AGENT); }
; __device__ __forceinline__ unsigned xb_add(unsigned* p, unsigned v) { return __hip_atomic_fetch_add(p, v, __ATOMIC_RELAXED, __HIP_MEMORY_SCOPE_AGENT); }
; #define XB_SPIN(cond, bar) do { unsigned _sp = 0; while (cond) { __builtin_amdgcn_s_sleep(1); \
;     if ((++_sp & 255u) == 0u) { if (xb_ld(&(bar)[XB_TMO])) break; if (_sp > XB_SPIN_CAP) { atomicAdd(&(bar)[XB_TMO], 1u); break; } } } } while (0)
; __device__ __forceinline__ void xcd_barrier(const XcdBarrier& b) {
;     ...
;         unsigned nloc = b.st[0], nx = b.st[1];
;         if (nloc == 0u) { xcd_barrier_complete(bar, b.x, nloc, nx); b.st[0] = nloc; b.st[1] = nx; }
;         const unsigned old = xb_add(&bar[XB_XSUB(b.x)], 1u);
;         const unsigned gen = old / nloc;
;         if (old + 1u == (gen + 1u) * nloc) {
;             __builtin_amdgcn_fence(__ATOMIC_RELEASE, "agent");
;             asm volatile("s_waitcnt vmcnt(0)" ::: "memory");
;             const unsigned og = xb_add(&bar[XB_TOP], 1u);
;             const unsigned tg = og / nx;
;             if (og + 1u == (tg + 1u) * nx) xb_add(&bar[XB_TOPGEN], 1u);
;             else XB_SPIN(xb_ld(&bar[XB_TOPGEN]) == tg, bar);
;             __builtin_amdgcn_fence(__ATOMIC_ACQUIRE, "agent");
;             xb_add(&bar[XB_XGEN(b.x)], 1u);
;             asm volatile("s_waitcnt vmcnt(0)" ::: "memory");
;         } else {
;             XB_SPIN(xb_ld(&bar[XB_XGEN(b.x)]) == gen, bar);
;             __builtin_amdgcn_fence(__ATOMIC_ACQUIRE, "agent");
;             asm volatile("s_waitcnt vmcnt(0)" ::: "memory");
.LBB0_255:
	s_or_b64 exec, exec, s[10:11]
	v_cvt_f32_u32_e32 v6, v4
	s_waitcnt vmcnt(0)
	v_readfirstlane_b32 s8, v5
	v_sub_u32_e32 v5, 0, v4
	v_rcp_iflag_f32_e32 v6, v6
	v_add_u32_e32 v7, s8, v3
	v_mul_f32_e32 v6, 0x4f7ffffe, v6
	v_cvt_u32_f32_e32 v6, v6
	v_mul_lo_u32 v3, v5, v6
	v_mul_hi_u32 v3, v6, v3
	v_add_u32_e32 v3, v6, v3
	v_mul_hi_u32 v3, v7, v3
	v_mul_lo_u32 v5, v3, v4
	v_sub_u32_e32 v5, v7, v5
	v_add_u32_e32 v6, 1, v3
	v_cmp_ge_u32_e32 vcc, v5, v4
	s_nop 1
	v_cndmask_b32_e32 v3, v3, v6, vcc
	v_sub_u32_e32 v6, v5, v4
	v_cndmask_b32_e32 v5, v5, v6, vcc
	v_add_u32_e32 v6, 1, v3
	v_cmp_ge_u32_e32 vcc, v5, v4
	v_add_u32_e32 v5, 1, v7
	s_nop 0
	v_cndmask_b32_e32 v3, v3, v6, vcc
	v_mul_lo_u32 v6, v4, v3
	v_add_u32_e32 v4, v6, v4
	v_mad_u32_u24 v255, v3, v2, v2
	v_cmp_ne_u32_e32 vcc, v5, v4
	s_and_saveexec_b64 s[8:9], vcc
	s_xor_b64 s[8:9], exec, s[8:9]
	s_cbranch_execz .LBB0_269
	buffer_inv sc1
	s_add_i32 s10, s28, 0x900
	s_mov_b32 s11, 0
	s_lshl_b64 s[10:11], s[10:11], 2
	s_add_u32 s14, s26, s10
	s_addc_u32 s15, s27, s11
	s_waitcnt lgkmcnt(0)
	v_mov_b32_e32 v2, 0
	global_load_dword v4, v2, s[14:15] sc1
	s_load_dword s101, s[0:1], 0x0
	s_load_dword s101, s[0:1], 0x40
	s_load_dword s101, s[0:1], 0x80
	s_load_dword s101, s[0:1], 0xc0
	s_waitcnt vmcnt(0)
	v_cmp_lt_u32_e32 vcc, v4, v255
	s_and_saveexec_b64 s[10:11], vcc
	s_cbranch_execz .LBB0_268
	s_add_u32 s12, s6, 0xc0200
	s_addc_u32 s13, s7, 0
	s_mov_b32 s29, 1
	s_mov_b64 s[16:17], 0
	s_branch .LBB0_259

; __device__ __forceinline__ unsigned xb_ld(unsigned* p)              { return __hip_atomic_load(p, __ATOMIC_RELAXED, __HIP_MEMORY_SCOPE_AGENT); }
; __device__ __forceinline__ unsigned xb_add(unsigned* p, unsigned v) { return __hip_atomic_fetch_add(p, v, __ATOMIC_RELAXED, __HIP_MEMORY_SCOPE_AGENT); }
; #define XB_SPIN(cond, bar) do { unsigned _sp = 0; while (cond) { __builtin_amdgcn_s_sleep(1); \
;     if ((++_sp & 255u) == 0u) { if (xb_ld(&(bar)[XB_TMO])) break; if (_sp > XB_SPIN_CAP) { atomicAdd(&(bar)[XB_TMO], 1u); break; } } } } while (0)
; __device__ __forceinline__ void xcd_barrier(const XcdBarrier& b) {
;     ...
;         if (old + 1u == (gen + 1u) * nloc) {
;             __builtin_amdgcn_fence(__ATOMIC_RELEASE, "agent");
;             asm volatile("s_waitcnt vmcnt(0)" ::: "memory");
;             const unsigned og = xb_add(&bar[XB_TOP], 1u);
;             const unsigned tg = og / nx;
;             if (og + 1u == (tg + 1u) * nx) xb_add(&bar[XB_TOPGEN], 1u);
;             else XB_SPIN(xb_ld(&bar[XB_TOPGEN]) == tg, bar);
;             __builtin_amdgcn_fence(__ATOMIC_ACQUIRE, "agent");
;             xb_add(&bar[XB_XGEN(b.x)], 1u);
;             asm volatile("s_waitcnt vmcnt(0)" ::: "memory");
.LBB0_269:
	s_andn2_saveexec_b64 s[8:9], s[8:9]
	s_cbranch_execz .LBB0_289
	s_mov_b64 s[8:9], exec
	buffer_wbl2 sc1
	buffer_inv sc1
	s_waitcnt lgkmcnt(0)
	s_waitcnt vmcnt(0)
	v_mbcnt_lo_u32_b32 v3, s8, 0
	v_mbcnt_hi_u32_b32 v3, s9, v3
	v_cmp_eq_u32_e32 vcc, 0, v3
	s_and_saveexec_b64 s[10:11], vcc
	s_cbranch_execz .LBB0_272
	s_bcnt1_i32_b64 s8, s[8:9]
	v_mov_b32_e32 v4, 0xc2400
	v_mov_b32_e32 v5, s8
	global_atomic_add v4, v5, s[6:7]
	global_atomic_add v4, v5, s[6:7] offset:256
	global_atomic_add v4, v5, s[6:7] offset:512
	global_atomic_add v4, v5, s[6:7] offset:768
	global_atomic_add v4, v5, s[6:7] offset:1024
	global_atomic_add v4, v5, s[6:7] offset:1280
	global_atomic_add v4, v5, s[6:7] offset:1536
	global_atomic_add v4, v5, s[6:7] offset:1792
	global_atomic_add v4, v5, s[6:7] offset:2048
	global_atomic_add v4, v5, s[6:7] offset:2304
	global_atomic_add v4, v5, s[6:7] offset:2560
	global_atomic_add v4, v5, s[6:7] offset:2816
	global_atomic_add v4, v5, s[6:7] offset:3072
	global_atomic_add v4, v5, s[6:7] offset:3328
	global_atomic_add v4, v5, s[6:7] offset:3584
	global_atomic_add v4, v5, s[6:7] offset:3840
	s_load_dword s101, s[0:1], 0x0
	s_load_dword s101, s[0:1], 0x40
	s_load_dword s101, s[0:1], 0x80
	s_load_dword s101, s[0:1], 0xc0

; __device__ __forceinline__ void ph_ret_chunk(unsigned char* lds_, bf16_t* Z, const bf16_t* KVF, const bf16_t* KVB, const float* decay_logit, const float* gn_w, int with_ctx, int u0, int ustep, unsigned* kvc, unsigned* barw) { PH_IDS;
;     ...
;     for (int u = u0; u < nunits; u += ustep) {
;         const bool lat = u < 256; const int bh = lat ? (u >> 3) : (u - 256), qb = lat ? (u & 7) : 0, b = bh >> 2, h = bh & 3;
;         const float lgf = -log1pf(__expf(-decay_logit[h])) * 1.4426950408889634f, lgb = -log1pf(__expf(-decay_logit[4 + h])) * 1.4426950408889634f;
;         const int qw0 = qb * 256 + wid * 32, qpos = qw0 + r32;
;         const int qrow = (lat ? b * 2048 : RL + b * 256) + qpos;
;         bf16_t* zq = Z + (size_t)qrow * ZW;
;         u32x4 sK[4], sV[4]; bf16x8 qf[4];
;         { const size_t rb = (lat ? (size_t)b * 2048 + qb * 256 : (size_t)RL + b * 256);
; #pragma unroll
;           for (int j = 0; j < 4; ++j) { const bf16_t* zr = Z + (rb + 64 * j + prow) * ZW + h * 64 + pc * 8; sK[j] = *(const u32x4*)(zr + C_RK); sV[j] = *(const u32x4*)(zr + C_RV); } }
; #pragma unroll
;         for (int st = 0; st < 4; ++st) qf[st] = *(const bf16x8*)(zq + C_RQ + h * 64 + 16 * st + 8 * hi);
;         if (kvc != nullptr && tid_ == 0) dep_spin(kvc, (unsigned)G_, barw);
.LBB0_745:
	s_cmpk_gt_i32 s50, 0xff
	s_cbranch_scc0 .LBB0_1047
	s_cmpk_gt_u32 s50, 0x11f
	s_cbranch_scc0 .LBB0_1013
	s_and_b64 vcc, exec, s[4:5]
	s_cbranch_vccz .LBB0_777
	s_cmpk_gt_u32 s50, 0x33f
	s_mov_b64 s[4:5], -1
	s_cbranch_scc0 .LBB0_765
	s_mov_b64 s[4:5], s[0:1]
	s_load_dwordx2 s[4:5], s[4:5], 0xf8
	s_mov_b64 s[6:7], s[0:1]
	s_mov_b64 s[8:9], s[0:1]
	s_load_dwordx2 s[6:7], s[6:7], 0xf8
	s_waitcnt lgkmcnt(0)
	s_add_u32 s10, s4, 0x4c00000
	s_addc_u32 s11, s5, 0
	s_mov_b64 s[4:5], s[0:1]
	s_load_dwordx2 s[8:9], s[8:9], 0xf0
	s_load_dwordx2 s[14:15], s[4:5], 0xc0
	s_mov_b64 s[4:5], s[0:1]
	s_mov_b64 s[12:13], s[0:1]
	v_mov_b32_e32 v43, v0
	s_mov_b32 s16, s2
	s_load_dwordx2 s[4:5], s[4:5], 0xc8
	s_and_b32 s22, s50, 3
	v_readfirstlane_b32 s20, v43
	s_ashr_i32 s16, s20, 1
	v_mov_b32_e32 v2, s16
	s_lshl_b32 s16, s22, 2
	s_mov_b32 s23, s3
	s_add_i32 s21, s50, 0xfffffcc0
	v_mov_b32_e32 v4, s16
	s_waitcnt lgkmcnt(0)
	global_load_dword v40, v4, s[14:15]
	global_load_dword v45, v4, s[14:15] offset:16
	s_lshl_b32 s14, s21, 6
	s_and_b32 s14, s14, 0x7fffff00
	v_bfi_b32 v74, s67, v2, v43
	s_add_i32 s56, s14, 0x4000
	v_add_u32_e32 v4, s56, v74
	v_ashrrev_i32_e32 v36, 3, v43
	v_and_b32_e32 v41, 7, v43
	v_ashrrev_i32_e32 v5, 31, v4
	v_ashrrev_i32_e32 v37, 31, v36
	v_lshlrev_b32_e32 v38, 4, v41
	v_mov_b32_e32 v39, v130
	v_lshlrev_b64 v[4:5], 12, v[4:5]
	v_lshl_add_u64 v[2:3], s[10:11], 0, v[38:39]
	v_lshl_add_u64 v[34:35], s[10:11], 0, v[4:5]
	v_lshl_add_u64 v[4:5], v[36:37], 0, s[56:57]
	s_lshl_b32 s56, s22, 7
	v_lshl_add_u64 v[2:3], v[2:3], 0, s[56:57]
	v_lshlrev_b64 v[4:5], 12, v[4:5]
	v_lshl_add_u64 v[26:27], v[2:3], 0, v[4:5]
	v_add_co_u32_e32 v14, vcc, s48, v26
	v_bfe_u32 v42, v43, 5, 1
	s_nop 0
	v_addc_co_u32_e32 v15, vcc, 0, v27, vcc
	v_add_co_u32_e32 v22, vcc, s49, v26
	v_lshl_add_u64 v[34:35], v[34:35], 0, s[56:57]
	s_nop 0
	v_addc_co_u32_e32 v23, vcc, 0, v27, vcc
	v_add_co_u32_e32 v30, vcc, 0xc0000, v26
	v_lshlrev_b32_e32 v70, 4, v42
	v_mov_b32_e32 v71, v130
	v_addc_co_u32_e32 v31, vcc, 0, v27, vcc
	v_lshl_add_u64 v[140:141], v[34:35], 0, v[70:71]
	global_load_dwordx4 v[6:9], v[26:27], off offset:832
	global_load_dwordx4 v[2:5], v[26:27], off offset:1344
	global_load_dwordx4 v[10:13], v[14:15], off offset:832
	s_nop 0
	global_load_dwordx4 v[14:17], v[14:15], off offset:1344
	s_nop 0
	global_load_dwordx4 v[18:21], v[22:23], off offset:832
	s_nop 0
	global_load_dwordx4 v[22:25], v[22:23], off offset:1344
	s_nop 0
	global_load_dwordx4 v[26:29], v[30:31], off offset:832
	s_nop 0
	global_load_dwordx4 v[30:33], v[30:31], off offset:1344
	s_nop 0
	global_load_dwordx4 v[66:69], v[140:141], off offset:2880
	global_load_dwordx4 v[136:139], v[140:141], off offset:2912
	global_load_dwordx4 v[132:135], v[140:141], off offset:2944
	global_load_dwordx4 v[126:129], v[140:141], off offset:2976
	s_bitcmp1_b32 s100, 0
	s_cbranch_scc1 .Lkvc_skip_a
	v_cmp_eq_u32_e32 vcc, 0, v43
	s_and_saveexec_b64 s[10:11], vcc
	s_cbranch_execz .LBB0_764
	s_load_dwordx2 s[12:13], s[12:13], 0xf8
	global_load_dword v37, v130, s[52:53] sc1
	s_waitcnt vmcnt(0)
	v_cmp_le_u32_e32 vcc, s23, v37
	s_cbranch_vccnz .LBB0_763
	s_waitcnt lgkmcnt(0)
	s_add_u32 s12, s12, 0xc0200
	s_addc_u32 s13, s13, 0
	s_mov_b32 s24, 1
	s_branch .LBB0_753

; __device__ __forceinline__ void ph_ret_chunk(unsigned char* lds_, bf16_t* Z, const bf16_t* KVF, const bf16_t* KVB, const float* decay_logit, const float* gn_w, int with_ctx, int u0, int ustep, unsigned* kvc, unsigned* barw) { PH_IDS;
;     ...
;         if (kvc != nullptr && tid_ == 0) dep_spin(kvc, (unsigned)G_, barw);
.LBB0_764:
	s_or_b64 exec, exec, s[10:11]
	s_bitset1_b32 s100, 0

; __device__ __forceinline__ void ph_ret_chunk(unsigned char* lds_, bf16_t* Z, const bf16_t* KVF, const bf16_t* KVB, const float* decay_logit, const float* gn_w, int with_ctx, int u0, int ustep, unsigned* kvc, unsigned* barw) { PH_IDS;
;     ...
;     for (int u = u0; u < nunits; u += ustep) {
;         const bool lat = u < 256; const int bh = lat ? (u >> 3) : (u - 256), qb = lat ? (u & 7) : 0, b = bh >> 2, h = bh & 3;
;         const float lgf = -log1pf(__expf(-decay_logit[h])) * 1.4426950408889634f, lgb = -log1pf(__expf(-decay_logit[4 + h])) * 1.4426950408889634f;
;         const int qw0 = qb * 256 + wid * 32, qpos = qw0 + r32;
;         const int qrow = (lat ? b * 2048 : RL + b * 256) + qpos;
;         bf16_t* zq = Z + (size_t)qrow * ZW;
;         u32x4 sK[4], sV[4]; bf16x8 qf[4];
;         { const size_t rb = (lat ? (size_t)b * 2048 + qb * 256 : (size_t)RL + b * 256);
; #pragma unroll
;           for (int j = 0; j < 4; ++j) { const bf16_t* zr = Z + (rb + 64 * j + prow) * ZW + h * 64 + pc * 8; sK[j] = *(const u32x4*)(zr + C_RK); sV[j] = *(const u32x4*)(zr + C_RV); } }
; #pragma unroll
;         for (int st = 0; st < 4; ++st) qf[st] = *(const bf16x8*)(zq + C_RQ + h * 64 + 16 * st + 8 * hi);
;         if (kvc != nullptr && tid_ == 0) dep_spin(kvc, (unsigned)G_, barw);
.LBB0_765:
	s_and_b64 vcc, exec, s[4:5]
	s_cbranch_vccz .LBB0_776
	s_mov_b64 s[4:5], s[0:1]
	s_load_dwordx2 s[6:7], s[4:5], 0xf8
	s_mov_b64 s[4:5], s[0:1]
	s_mov_b64 s[8:9], s[0:1]
	s_load_dwordx2 s[4:5], s[4:5], 0xf8
	s_waitcnt lgkmcnt(0)
	s_add_u32 s12, s6, 0x4c00000
	s_addc_u32 s13, s7, 0
	s_load_dwordx2 s[6:7], s[8:9], 0xf0
	s_mov_b64 s[8:9], s[0:1]
	s_mov_b64 s[10:11], s[0:1]
	s_load_dwordx2 s[8:9], s[8:9], 0xc0
	s_load_dwordx2 s[20:21], s[10:11], 0xc8
	s_mov_b64 s[10:11], s[0:1]
	v_mov_b32_e32 v123, v0
	s_mov_b32 s14, s2
	s_add_i32 s18, s50, 0xfffffdc0
	v_readfirstlane_b32 s39, v123
	s_ashr_i32 s14, s39, 1
	v_mov_b32_e32 v2, s14
	s_and_b32 s43, s50, 7
	s_bfe_u32 s19, s18, 0x20003
	s_waitcnt vmcnt(7)
	v_bfi_b32 v160, s67, v2, v123
	s_lshl_b32 s14, s19, 2
	s_lshl_b32 s38, s43, 8
	s_mov_b32 s22, s3
	s_lshr_b32 s56, s18, 5
	v_mov_b32_e32 v4, s14
	v_add_u32_e32 v131, s38, v160
	s_waitcnt lgkmcnt(0)
	global_load_dword v48, v4, s[8:9]
	global_load_dword v47, v4, s[8:9] offset:16
	v_lshl_add_u32 v4, s56, 11, v131
	v_ashrrev_i32_e32 v38, 3, v123
	v_and_b32_e32 v46, 7, v123
	v_ashrrev_i32_e32 v5, 31, v4
	s_lshl_b64 s[8:9], s[56:57], 11
	v_ashrrev_i32_e32 v39, 31, v38
	v_lshlrev_b32_e32 v86, 4, v46
	v_mov_b32_e32 v87, v130
	v_lshlrev_b64 v[4:5], 12, v[4:5]
	s_or_b32 s8, s8, s38
	v_lshl_add_u64 v[2:3], s[12:13], 0, v[86:87]
	v_lshl_add_u64 v[34:35], s[12:13], 0, v[4:5]
	v_lshl_add_u64 v[4:5], s[8:9], 0, v[38:39]
	s_lshl_b32 s56, s19, 7
	v_lshl_add_u64 v[2:3], v[2:3], 0, s[56:57]
	v_lshlrev_b64 v[4:5], 12, v[4:5]
	v_lshl_add_u64 v[26:27], v[2:3], 0, v[4:5]
	v_add_co_u32_e32 v14, vcc, s48, v26
	v_bfe_u32 v122, v123, 5, 1
	s_nop 0
	v_addc_co_u32_e32 v15, vcc, 0, v27, vcc
	v_add_co_u32_e32 v22, vcc, s49, v26
	v_lshl_add_u64 v[80:81], v[34:35], 0, s[56:57]
	s_nop 0
	v_addc_co_u32_e32 v23, vcc, 0, v27, vcc
	v_add_co_u32_e32 v30, vcc, 0xc0000, v26
	v_lshlrev_b32_e32 v78, 4, v122
	v_mov_b32_e32 v79, v130
	v_addc_co_u32_e32 v31, vcc, 0, v27, vcc
	v_lshl_add_u64 v[140:141], v[80:81], 0, v[78:79]
	global_load_dwordx4 v[6:9], v[26:27], off offset:832
	global_load_dwordx4 v[2:5], v[26:27], off offset:1344
	global_load_dwordx4 v[10:13], v[14:15], off offset:832
	s_nop 0
	global_load_dwordx4 v[14:17], v[14:15], off offset:1344
	s_nop 0
	global_load_dwordx4 v[18:21], v[22:23], off offset:832
	s_nop 0
	global_load_dwordx4 v[22:25], v[22:23], off offset:1344
	s_nop 0
	global_load_dwordx4 v[26:29], v[30:31], off offset:832
	s_nop 0
	global_load_dwordx4 v[30:33], v[30:31], off offset:1344
	s_nop 0
	global_load_dwordx4 v[66:69], v[140:141], off offset:2880
	global_load_dwordx4 v[102:105], v[140:141], off offset:2912
	global_load_dwordx4 v[98:101], v[140:141], off offset:2944
	global_load_dwordx4 v[94:97], v[140:141], off offset:2976
	s_bitcmp1_b32 s100, 0
	s_cbranch_scc1 .Lkvc_skip_b
	v_cmp_eq_u32_e32 vcc, 0, v123
	s_and_saveexec_b64 s[8:9], vcc
	s_cbranch_execz .LBB0_1098
	s_load_dwordx2 s[10:11], s[10:11], 0xf8
	global_load_dword v34, v130, s[52:53] sc1
	s_waitcnt vmcnt(0)
	v_cmp_le_u32_e32 vcc, s22, v34
	s_cbranch_vccnz .LBB0_1097
	s_waitcnt lgkmcnt(0)
	s_add_u32 s10, s10, 0xc0200
	s_addc_u32 s11, s11, 0
	s_mov_b32 s23, 1
	s_branch .LBB0_770

; __device__ __forceinline__ void ph_ret_chunk(unsigned char* lds_, bf16_t* Z, const bf16_t* KVF, const bf16_t* KVB, const float* decay_logit, const float* gn_w, int with_ctx, int u0, int ustep, unsigned* kvc, unsigned* barw) { PH_IDS;
;     ...
;         if (kvc != nullptr && tid_ == 0) dep_spin(kvc, (unsigned)G_, barw);
.LBB0_1098:
	s_or_b64 exec, exec, s[8:9]
	s_bitset1_b32 s100, 0

; __device__ __forceinline__ unsigned xb_ld(unsigned* p)              { return __hip_atomic_load(p, __ATOMIC_RELAXED, __HIP_MEMORY_SCOPE_AGENT); }
; __device__ __forceinline__ unsigned xb_add(unsigned* p, unsigned v) { return __hip_atomic_fetch_add(p, v, __ATOMIC_RELAXED, __HIP_MEMORY_SCOPE_AGENT); }
; #define XB_SPIN(cond, bar) do { unsigned _sp = 0; while (cond) { __builtin_amdgcn_s_sleep(1); \
;     if ((++_sp & 255u) == 0u) { if (xb_ld(&(bar)[XB_TMO])) break; if (_sp > XB_SPIN_CAP) { atomicAdd(&(bar)[XB_TMO], 1u); break; } } } } while (0)
; __device__ __forceinline__ void xcd_barrier(const XcdBarrier& b) {
;     ...
;         unsigned nloc = b.st[0], nx = b.st[1];
;         if (nloc == 0u) { xcd_barrier_complete(bar, b.x, nloc, nx); b.st[0] = nloc; b.st[1] = nx; }
;         const unsigned old = xb_add(&bar[XB_XSUB(b.x)], 1u);
;         const unsigned gen = old / nloc;
;         if (old + 1u == (gen + 1u) * nloc) {
;             __builtin_amdgcn_fence(__ATOMIC_RELEASE, "agent");
;             asm volatile("s_waitcnt vmcnt(0)" ::: "memory");
;             const unsigned og = xb_add(&bar[XB_TOP], 1u);
;             const unsigned tg = og / nx;
;             if (og + 1u == (tg + 1u) * nx) xb_add(&bar[XB_TOPGEN], 1u);
;             else XB_SPIN(xb_ld(&bar[XB_TOPGEN]) == tg, bar);
;             __builtin_amdgcn_fence(__ATOMIC_ACQUIRE, "agent");
;             xb_add(&bar[XB_XGEN(b.x)], 1u);
;             asm volatile("s_waitcnt vmcnt(0)" ::: "memory");
;         } else {
;             XB_SPIN(xb_ld(&bar[XB_XGEN(b.x)]) == gen, bar);
;             __builtin_amdgcn_fence(__ATOMIC_ACQUIRE, "agent");
;             asm volatile("s_waitcnt vmcnt(0)" ::: "memory");
.LBB0_1619:
	s_or_b64 exec, exec, s[16:17]
	v_cvt_f32_u32_e32 v6, v4
	s_waitcnt vmcnt(0)
	v_readfirstlane_b32 s10, v5
	v_sub_u32_e32 v5, 0, v4
	v_rcp_iflag_f32_e32 v6, v6
	v_add_u32_e32 v7, s10, v3
	v_mul_f32_e32 v6, 0x4f7ffffe, v6
	v_cvt_u32_f32_e32 v6, v6
	v_mul_lo_u32 v3, v5, v6
	v_mul_hi_u32 v3, v6, v3
	v_add_u32_e32 v3, v6, v3
	v_mul_hi_u32 v3, v7, v3
	v_mul_lo_u32 v5, v3, v4
	v_sub_u32_e32 v5, v7, v5
	v_add_u32_e32 v6, 1, v3
	v_cmp_ge_u32_e32 vcc, v5, v4
	s_nop 1
	v_cndmask_b32_e32 v3, v3, v6, vcc
	v_sub_u32_e32 v6, v5, v4
	v_cndmask_b32_e32 v5, v5, v6, vcc
	v_add_u32_e32 v6, 1, v3
	v_cmp_ge_u32_e32 vcc, v5, v4
	v_add_u32_e32 v5, 1, v7
	s_nop 0
	v_cndmask_b32_e32 v3, v3, v6, vcc
	v_mul_lo_u32 v6, v4, v3
	v_add_u32_e32 v4, v6, v4
	v_mad_u32_u24 v255, v3, v2, v2
	v_cmp_ne_u32_e32 vcc, v5, v4
	s_and_saveexec_b64 s[10:11], vcc
	s_xor_b64 s[10:11], exec, s[10:11]
	s_cbranch_execz .LBB0_1633
	buffer_inv sc1
	s_add_i32 s16, s36, 0x900
	s_mov_b32 s17, 0
	s_lshl_b64 s[16:17], s[16:17], 2
	s_add_u32 s20, s34, s16
	s_addc_u32 s21, s35, s17
	s_waitcnt lgkmcnt(0)
	v_mov_b32_e32 v2, 0
	global_load_dword v4, v2, s[20:21] sc1
	s_load_dword s101, s[0:1], 0x0
	s_load_dword s101, s[0:1], 0x40
	s_load_dword s101, s[0:1], 0x80
	s_load_dword s101, s[0:1], 0xc0
	s_waitcnt vmcnt(0)
	v_cmp_lt_u32_e32 vcc, v4, v255
	s_and_saveexec_b64 s[16:17], vcc
	s_cbranch_execz .LBB0_1632
	s_add_u32 s18, s8, 0xc0200
	s_addc_u32 s19, s9, 0
	s_mov_b32 s37, 1
	s_mov_b64 s[22:23], 0
	s_branch .LBB0_1623

; __device__ __forceinline__ unsigned xb_ld(unsigned* p)              { return __hip_atomic_load(p, __ATOMIC_RELAXED, __HIP_MEMORY_SCOPE_AGENT); }
; __device__ __forceinline__ unsigned xb_add(unsigned* p, unsigned v) { return __hip_atomic_fetch_add(p, v, __ATOMIC_RELAXED, __HIP_MEMORY_SCOPE_AGENT); }
; #define XB_SPIN(cond, bar) do { unsigned _sp = 0; while (cond) { __builtin_amdgcn_s_sleep(1); \
;     if ((++_sp & 255u) == 0u) { if (xb_ld(&(bar)[XB_TMO])) break; if (_sp > XB_SPIN_CAP) { atomicAdd(&(bar)[XB_TMO], 1u); break; } } } } while (0)
; __device__ __forceinline__ void xcd_barrier(const XcdBarrier& b) {
;     ...
;         if (old + 1u == (gen + 1u) * nloc) {
;             __builtin_amdgcn_fence(__ATOMIC_RELEASE, "agent");
;             asm volatile("s_waitcnt vmcnt(0)" ::: "memory");
;             const unsigned og = xb_add(&bar[XB_TOP], 1u);
;             const unsigned tg = og / nx;
;             if (og + 1u == (tg + 1u) * nx) xb_add(&bar[XB_TOPGEN], 1u);
;             else XB_SPIN(xb_ld(&bar[XB_TOPGEN]) == tg, bar);
;             __builtin_amdgcn_fence(__ATOMIC_ACQUIRE, "agent");
;             xb_add(&bar[XB_XGEN(b.x)], 1u);
;             asm volatile("s_waitcnt vmcnt(0)" ::: "memory");
.LBB0_1633:
	s_andn2_saveexec_b64 s[10:11], s[10:11]
	s_cbranch_execz .LBB0_1653
	s_mov_b64 s[10:11], exec
	buffer_wbl2 sc1
	buffer_inv sc1
	s_waitcnt lgkmcnt(0)
	s_waitcnt vmcnt(0)
	v_mbcnt_lo_u32_b32 v3, s10, 0
	v_mbcnt_hi_u32_b32 v3, s11, v3
	v_cmp_eq_u32_e32 vcc, 0, v3
	s_and_saveexec_b64 s[16:17], vcc
	s_cbranch_execz .LBB0_1636
	s_bcnt1_i32_b64 s10, s[10:11]
	v_mov_b32_e32 v4, 0xc2400
	v_mov_b32_e32 v5, s10
	global_atomic_add v4, v5, s[8:9]
	global_atomic_add v4, v5, s[8:9] offset:256
	global_atomic_add v4, v5, s[8:9] offset:512
	global_atomic_add v4, v5, s[8:9] offset:768
	global_atomic_add v4, v5, s[8:9] offset:1024
	global_atomic_add v4, v5, s[8:9] offset:1280
	global_atomic_add v4, v5, s[8:9] offset:1536
	global_atomic_add v4, v5, s[8:9] offset:1792
	global_atomic_add v4, v5, s[8:9] offset:2048
	global_atomic_add v4, v5, s[8:9] offset:2304
	global_atomic_add v4, v5, s[8:9] offset:2560
	global_atomic_add v4, v5, s[8:9] offset:2816
	global_atomic_add v4, v5, s[8:9] offset:3072
	global_atomic_add v4, v5, s[8:9] offset:3328
	global_atomic_add v4, v5, s[8:9] offset:3584
	global_atomic_add v4, v5, s[8:9] offset:3840
	s_load_dword s101, s[0:1], 0x0
	s_load_dword s101, s[0:1], 0x40
	s_load_dword s101, s[0:1], 0x80
	s_load_dword s101, s[0:1], 0xc0

; __device__ __forceinline__ void ph_ret_chunk(unsigned char* lds_, bf16_t* Z, const bf16_t* KVF, const bf16_t* KVB, const float* decay_logit, const float* gn_w, int with_ctx, int u0, int ustep, unsigned* kvc, unsigned* barw) { PH_IDS;
;     ...
;     for (int u = u0; u < nunits; u += ustep) {
;         const bool lat = u < 256; const int bh = lat ? (u >> 3) : (u - 256), qb = lat ? (u & 7) : 0, b = bh >> 2, h = bh & 3;
;         const float lgf = -log1pf(__expf(-decay_logit[h])) * 1.4426950408889634f, lgb = -log1pf(__expf(-decay_logit[4 + h])) * 1.4426950408889634f;
;         const int qw0 = qb * 256 + wid * 32, qpos = qw0 + r32;
;         const int qrow = (lat ? b * 2048 : RL + b * 256) + qpos;
;         bf16_t* zq = Z + (size_t)qrow * ZW;
;         u32x4 sK[4], sV[4]; bf16x8 qf[4];
;         { const size_t rb = (lat ? (size_t)b * 2048 + qb * 256 : (size_t)RL + b * 256);
; #pragma unroll
;           for (int j = 0; j < 4; ++j) { const bf16_t* zr = Z + (rb + 64 * j + prow) * ZW + h * 64 + pc * 8; sK[j] = *(const u32x4*)(zr + C_RK); sV[j] = *(const u32x4*)(zr + C_RV); } }
; #pragma unroll
;         for (int st = 0; st < 4; ++st) qf[st] = *(const bf16x8*)(zq + C_RQ + h * 64 + 16 * st + 8 * hi);
;         if (kvc != nullptr && tid_ == 0) dep_spin(kvc, (unsigned)G_, barw);
.LBB0_2571:
	s_cmpk_gt_i32 s89, 0xff
	s_cbranch_scc0 .LBB0_2959
	s_and_b64 vcc, exec, s[4:5]
	s_cbranch_vccz .LBB0_2731
	s_mov_b64 s[4:5], s[0:1]
	s_load_dwordx2 s[6:7], s[4:5], 0xf8
	s_mov_b64 s[4:5], s[0:1]
	s_mov_b64 s[8:9], s[0:1]
	s_load_dwordx2 s[4:5], s[4:5], 0xf8
	s_waitcnt lgkmcnt(0)
	s_add_u32 s12, s6, 0x4c00000
	s_addc_u32 s13, s7, 0
	s_load_dwordx2 s[6:7], s[8:9], 0xf0
	s_mov_b64 s[8:9], s[0:1]
	s_mov_b64 s[10:11], s[0:1]
	s_load_dwordx2 s[8:9], s[8:9], 0xc0
	s_load_dwordx2 s[20:21], s[10:11], 0xc8
	s_mov_b64 s[10:11], s[0:1]
	v_mov_b32_e32 v123, v0
	s_mov_b32 s14, s2
	s_add_i32 s18, s89, 0xfffffe00
	v_readfirstlane_b32 s42, v123
	s_ashr_i32 s14, s42, 1
	v_mov_b32_e32 v2, s14
	s_and_b32 s43, s89, 7
	s_bfe_u32 s19, s18, 0x20003
	s_waitcnt vmcnt(7)
	v_bfi_b32 v160, s59, v2, v123
	s_lshl_b32 s14, s19, 2
	s_lshl_b32 s38, s43, 8
	s_mov_b32 s22, s3
	s_lshr_b32 s54, s18, 5
	v_mov_b32_e32 v4, s14
	v_add_u32_e32 v131, s38, v160
	s_waitcnt lgkmcnt(0)
	global_load_dword v48, v4, s[8:9] offset:32
	global_load_dword v47, v4, s[8:9] offset:48
	v_lshl_add_u32 v4, s54, 11, v131
	v_ashrrev_i32_e32 v38, 3, v123
	v_and_b32_e32 v46, 7, v123
	v_ashrrev_i32_e32 v5, 31, v4
	s_lshl_b64 s[8:9], s[54:55], 11
	v_ashrrev_i32_e32 v39, 31, v38
	v_lshlrev_b32_e32 v86, 4, v46
	v_mov_b32_e32 v87, v130
	v_lshlrev_b64 v[4:5], 12, v[4:5]
	s_or_b32 s8, s8, s38
	v_lshl_add_u64 v[2:3], s[12:13], 0, v[86:87]
	v_lshl_add_u64 v[34:35], s[12:13], 0, v[4:5]
	v_lshl_add_u64 v[4:5], s[8:9], 0, v[38:39]
	s_lshl_b32 s54, s19, 7
	v_lshl_add_u64 v[2:3], v[2:3], 0, s[54:55]
	v_lshlrev_b64 v[4:5], 12, v[4:5]
	v_lshl_add_u64 v[26:27], v[2:3], 0, v[4:5]
	s_mov_b32 s8, 0x40000
	v_add_co_u32_e32 v14, vcc, s8, v26
	s_mov_b32 s8, 0x80000
	s_nop 0
	v_addc_co_u32_e32 v15, vcc, 0, v27, vcc
	v_add_co_u32_e32 v22, vcc, s8, v26
	v_bfe_u32 v122, v123, 5, 1
	s_nop 0
	v_addc_co_u32_e32 v23, vcc, 0, v27, vcc
	v_add_co_u32_e32 v30, vcc, 0xc0000, v26
	v_lshl_add_u64 v[80:81], v[34:35], 0, s[54:55]
	v_lshlrev_b32_e32 v78, 4, v122
	v_mov_b32_e32 v79, v130
	v_addc_co_u32_e32 v31, vcc, 0, v27, vcc
	v_lshl_add_u64 v[140:141], v[80:81], 0, v[78:79]
	global_load_dwordx4 v[6:9], v[26:27], off offset:832
	global_load_dwordx4 v[2:5], v[26:27], off offset:1344
	global_load_dwordx4 v[10:13], v[14:15], off offset:832
	s_nop 0
	global_load_dwordx4 v[14:17], v[14:15], off offset:1344
	s_nop 0
	global_load_dwordx4 v[18:21], v[22:23], off offset:832
	s_nop 0
	global_load_dwordx4 v[22:25], v[22:23], off offset:1344
	s_nop 0
	global_load_dwordx4 v[26:29], v[30:31], off offset:832
	s_nop 0
	global_load_dwordx4 v[30:33], v[30:31], off offset:1344
	s_nop 0
	global_load_dwordx4 v[66:69], v[140:141], off offset:2880
	global_load_dwordx4 v[102:105], v[140:141], off offset:2912
	global_load_dwordx4 v[98:101], v[140:141], off offset:2944
	global_load_dwordx4 v[94:97], v[140:141], off offset:2976
	s_bitcmp1_b32 s100, 1
	s_cbranch_scc1 .Lkvc_skip_c
	v_cmp_eq_u32_e32 vcc, 0, v123
	s_and_saveexec_b64 s[8:9], vcc
	s_cbranch_execz .LBB0_2588
	s_load_dwordx2 s[10:11], s[10:11], 0xf8
	global_load_dword v34, v130, s[50:51] sc1
	s_waitcnt vmcnt(0)
	v_cmp_le_u32_e32 vcc, s22, v34
	s_cbranch_vccnz .LBB0_2587
	s_waitcnt lgkmcnt(0)
	s_add_u32 s10, s10, 0xc0200
	s_addc_u32 s11, s11, 0
	s_mov_b32 s23, 1
	s_branch .LBB0_2577

; __device__ __forceinline__ void ph_ret_chunk(unsigned char* lds_, bf16_t* Z, const bf16_t* KVF, const bf16_t* KVB, const float* decay_logit, const float* gn_w, int with_ctx, int u0, int ustep, unsigned* kvc, unsigned* barw) { PH_IDS;
;     ...
;         if (kvc != nullptr && tid_ == 0) dep_spin(kvc, (unsigned)G_, barw);
.LBB0_2588:
	s_or_b64 exec, exec, s[8:9]
	s_bitset1_b32 s100, 1

; __device__ __forceinline__ unsigned xb_ld(unsigned* p)              { return __hip_atomic_load(p, __ATOMIC_RELAXED, __HIP_MEMORY_SCOPE_AGENT); }
; __device__ __forceinline__ unsigned xb_add(unsigned* p, unsigned v) { return __hip_atomic_fetch_add(p, v, __ATOMIC_RELAXED, __HIP_MEMORY_SCOPE_AGENT); }
; #define XB_SPIN(cond, bar) do { unsigned _sp = 0; while (cond) { __builtin_amdgcn_s_sleep(1); \
;     if ((++_sp & 255u) == 0u) { if (xb_ld(&(bar)[XB_TMO])) break; if (_sp > XB_SPIN_CAP) { atomicAdd(&(bar)[XB_TMO], 1u); break; } } } } while (0)
; __device__ __forceinline__ void xcd_barrier(const XcdBarrier& b) {
;     ...
;         unsigned nloc = b.st[0], nx = b.st[1];
;         if (nloc == 0u) { xcd_barrier_complete(bar, b.x, nloc, nx); b.st[0] = nloc; b.st[1] = nx; }
;         const unsigned old = xb_add(&bar[XB_XSUB(b.x)], 1u);
;         const unsigned gen = old / nloc;
;         if (old + 1u == (gen + 1u) * nloc) {
;             __builtin_amdgcn_fence(__ATOMIC_RELEASE, "agent");
;             asm volatile("s_waitcnt vmcnt(0)" ::: "memory");
;             const unsigned og = xb_add(&bar[XB_TOP], 1u);
;             const unsigned tg = og / nx;
;             if (og + 1u == (tg + 1u) * nx) xb_add(&bar[XB_TOPGEN], 1u);
;             else XB_SPIN(xb_ld(&bar[XB_TOPGEN]) == tg, bar);
;             __builtin_amdgcn_fence(__ATOMIC_ACQUIRE, "agent");
;             xb_add(&bar[XB_XGEN(b.x)], 1u);
;             asm volatile("s_waitcnt vmcnt(0)" ::: "memory");
;         } else {
;             XB_SPIN(xb_ld(&bar[XB_XGEN(b.x)]) == gen, bar);
;             __builtin_amdgcn_fence(__ATOMIC_ACQUIRE, "agent");
;             asm volatile("s_waitcnt vmcnt(0)" ::: "memory");
.LBB0_3173:
	s_or_b64 exec, exec, s[10:11]
	v_cvt_f32_u32_e32 v6, v4
	s_waitcnt vmcnt(0)
	v_readfirstlane_b32 s8, v5
	v_sub_u32_e32 v5, 0, v4
	v_rcp_iflag_f32_e32 v6, v6
	v_add_u32_e32 v7, s8, v3
	v_mul_f32_e32 v6, 0x4f7ffffe, v6
	v_cvt_u32_f32_e32 v6, v6
	v_mul_lo_u32 v3, v5, v6
	v_mul_hi_u32 v3, v6, v3
	v_add_u32_e32 v3, v6, v3
	v_mul_hi_u32 v3, v7, v3
	v_mul_lo_u32 v5, v3, v4
	v_sub_u32_e32 v5, v7, v5
	v_add_u32_e32 v6, 1, v3
	v_cmp_ge_u32_e32 vcc, v5, v4
	s_nop 1
	v_cndmask_b32_e32 v3, v3, v6, vcc
	v_sub_u32_e32 v6, v5, v4
	v_cndmask_b32_e32 v5, v5, v6, vcc
	v_add_u32_e32 v6, 1, v3
	v_cmp_ge_u32_e32 vcc, v5, v4
	v_add_u32_e32 v5, 1, v7
	s_nop 0
	v_cndmask_b32_e32 v3, v3, v6, vcc
	v_mul_lo_u32 v6, v4, v3
	v_add_u32_e32 v4, v6, v4
	v_mad_u32_u24 v255, v3, v2, v2
	v_cmp_ne_u32_e32 vcc, v5, v4
	s_and_saveexec_b64 s[8:9], vcc
	s_xor_b64 s[8:9], exec, s[8:9]
	s_cbranch_execz .LBB0_3187
	buffer_inv sc1
	s_add_i32 s10, s30, 0x900
	s_mov_b32 s11, 0
	s_lshl_b64 s[10:11], s[10:11], 2
	s_add_u32 s16, s28, s10
	s_addc_u32 s17, s29, s11
	s_waitcnt lgkmcnt(0)
	v_mov_b32_e32 v2, 0
	global_load_dword v4, v2, s[16:17] sc1
	s_load_dword s101, s[0:1], 0x0
	s_load_dword s101, s[0:1], 0x40
	s_load_dword s101, s[0:1], 0x80
	s_load_dword s101, s[0:1], 0xc0
	s_waitcnt vmcnt(0)
	v_cmp_lt_u32_e32 vcc, v4, v255
	s_and_saveexec_b64 s[10:11], vcc
	s_cbranch_execz .LBB0_3186
	s_add_u32 s14, s6, 0xc0200
	s_addc_u32 s15, s7, 0
	s_mov_b32 s31, 1
	s_mov_b64 s[18:19], 0
	s_branch .LBB0_3177
